# MLA role split completed: waves 4-7 are pure consumers in the tile loop (no global loads, LDS writes or vmcnt wait); waves 0-3 stage both halves of K and V plus the rope keys (5 loads per tile)
# speedup vs baseline: 1.0028x; 1.0028x over previous
.Lmla_p_nomask:
	v_max3_f32 v251, v64, v65, v66
	v_max3_f32 v251, v251, v67, v68
	v_max3_f32 v251, v251, v69, v70
	v_max3_f32 v251, v251, v71, v72
	v_max3_f32 v251, v251, v73, v74
	v_max3_f32 v251, v251, v75, v76
	v_max3_f32 v251, v251, v77, v78
	v_max_f32_e32 v251, v251, v79
	v_max3_f32 v252, v80, v81, v82
	v_max3_f32 v252, v252, v83, v84
	v_max3_f32 v252, v252, v85, v86
	v_max3_f32 v252, v252, v87, v88
	v_max3_f32 v252, v252, v89, v90
	v_max3_f32 v252, v252, v91, v92
	v_max3_f32 v252, v252, v93, v94
	v_max_f32_e32 v252, v252, v95
	v_max_f32_e32 v251, v251, v252
	v_mov_b32_e32 v252, v251
	s_nop 1
	v_permlane32_swap_b32_e32 v251, v252
	v_max_f32_e32 v251, v251, v252
	v_mov_b32_e32 v212, v251
	v_sub_f32_e32 v64, v64, v251
	v_sub_f32_e32 v65, v65, v251
	v_sub_f32_e32 v66, v66, v251
	v_sub_f32_e32 v67, v67, v251
	v_sub_f32_e32 v68, v68, v251
	v_sub_f32_e32 v69, v69, v251
	v_sub_f32_e32 v70, v70, v251
	v_sub_f32_e32 v71, v71, v251
	v_sub_f32_e32 v72, v72, v251
	v_sub_f32_e32 v73, v73, v251
	v_sub_f32_e32 v74, v74, v251
	v_sub_f32_e32 v75, v75, v251
	v_sub_f32_e32 v76, v76, v251
	v_sub_f32_e32 v77, v77, v251
	v_sub_f32_e32 v78, v78, v251
	v_sub_f32_e32 v79, v79, v251
	v_sub_f32_e32 v80, v80, v251
	v_sub_f32_e32 v81, v81, v251
	v_sub_f32_e32 v82, v82, v251
	v_sub_f32_e32 v83, v83, v251
	v_sub_f32_e32 v84, v84, v251
	v_sub_f32_e32 v85, v85, v251
	v_sub_f32_e32 v86, v86, v251
	v_sub_f32_e32 v87, v87, v251
	v_sub_f32_e32 v88, v88, v251
	v_sub_f32_e32 v89, v89, v251
	v_sub_f32_e32 v90, v90, v251
	v_sub_f32_e32 v91, v91, v251
	v_sub_f32_e32 v92, v92, v251
	v_sub_f32_e32 v93, v93, v251
	v_sub_f32_e32 v94, v94, v251
	v_sub_f32_e32 v95, v95, v251
	v_xor_b32_e32 v48, 0x80000000, v251
	v_mov_b32_e32 v49, v48
	v_mov_b32_e32 v50, v48
	v_mov_b32_e32 v51, v48
	v_mov_b32_e32 v52, v48
	v_mov_b32_e32 v53, v48
	v_mov_b32_e32 v54, v48
	v_mov_b32_e32 v55, v48
	v_mov_b32_e32 v56, v48
	v_mov_b32_e32 v57, v48
	v_mov_b32_e32 v58, v48
	v_mov_b32_e32 v59, v48
	v_mov_b32_e32 v60, v48
	v_mov_b32_e32 v61, v48
	v_mov_b32_e32 v62, v48
	v_mov_b32_e32 v63, v48
	s_mov_b64 s[6:7], 0x30000
	v_lshl_add_u64 v[200:201], v[192:193], 0, s[6:7]
	global_load_dwordx4 v[222:225], v[200:201], off
	s_mov_b64 s[6:7], 0x50000
	v_lshl_add_u64 v[200:201], v[190:191], 0, s[6:7]
	global_load_dwordx4 v[246:249], v[200:201], off
	s_waitcnt lgkmcnt(0)
	s_barrier
	s_cmp_lt_u32 s39, 4
	s_cbranch_scc0 .Lmla_loopb
.Lmla_loopa:
.Lmla_it0a:
	s_add_i32 s42, s65, 3
	s_min_u32 s42, s42, s44
	s_lshl_b64 s[6:7], s[42:43], 17
	v_lshl_add_u64 v[14:15], v[190:191], 0, s[6:7]
	s_lshl_b64 s[6:7], s[42:43], 12
	v_lshl_add_u64 v[252:253], v[194:195], 0, s[6:7]
	s_add_i32 s42, s65, 2
	s_min_u32 s42, s42, s44
	s_lshl_b64 s[6:7], s[42:43], 17
	v_lshl_add_u64 v[250:251], v[192:193], 0, s[6:7]
	s_mov_b64 s[4:5], 0x10000
	v_lshl_add_u64 v[200:201], v[250:251], 0, s[4:5]
	global_load_dwordx4 v[6:9], v[14:15], off
	v_lshl_add_u64 v[14:15], v[14:15], 0, s[4:5]
	global_load_dwordx4 v[10:13], v[250:251], off
	global_load_dwordx4 v[218:221], v[200:201], off
	global_load_dwordx4 v[242:245], v[14:15], off
	global_load_dwordx4 v[2:5], v[252:253], off
	s_cmp_ge_u32 s65, s45
	s_cbranch_scc1 .Lmla_skip0a
	s_add_i32 s41, s65, 1
	s_cmp_ge_u32 s41, s64
	s_cselect_b32 s7, 1, 0
	s_cmp_lt_u32 s41, s45
	s_cselect_b32 s26, 1, 0
	s_and_b32 s56, s7, s26
	s_lshl_b32 s27, s41, 6
	ds_read_b128 v[164:167], v210 offset:25600
	ds_read_b128 v[168:171], v210 offset:25632
	ds_read_b128 v[172:175], v210 offset:25664
	ds_read_b128 v[214:217], v210 offset:25696
	s_setprio 3
	v_exp_f32_e32 v64, v64
	v_exp_f32_e32 v65, v65
	v_exp_f32_e32 v66, v66
	v_exp_f32_e32 v67, v67
	s_waitcnt lgkmcnt(3)
	v_mfma_f32_32x32x16_bf16 v[132:147], v[164:167], v[96:99], v[48:63]
	ds_read_b128 v[164:167], v210 offset:25728
	v_add_f32_e32 v14, v64, v65
	v_add_f32_e32 v15, v66, v67
	v_exp_f32_e32 v68, v68
	v_exp_f32_e32 v69, v69
	s_waitcnt lgkmcnt(3)
	v_mfma_f32_32x32x16_bf16 v[132:147], v[168:171], v[100:103], v[132:147]
	ds_read_b128 v[168:171], v210 offset:25760
	v_exp_f32_e32 v70, v70
	v_exp_f32_e32 v71, v71
	v_add_f32_e32 v14, v14, v15
	v_add_f32_e32 v15, v68, v69
	s_waitcnt lgkmcnt(3)
	v_mfma_f32_32x32x16_bf16 v[132:147], v[172:175], v[104:107], v[132:147]
	ds_read_b128 v[172:175], v210 offset:32256
	v_add_f32_e32 v213, v70, v71
	v_cvt_pk_bf16_f32 v64, v64, v65
	v_cvt_pk_bf16_f32 v65, v66, v67
	v_cvt_pk_bf16_f32 v66, v68, v69
	v_cvt_pk_bf16_f32 v67, v70, v71
	s_waitcnt lgkmcnt(3)
	v_mfma_f32_32x32x16_bf16 v[132:147], v[214:217], v[108:111], v[132:147]
	ds_read_b128 v[214:217], v210 offset:32288
	v_exp_f32_e32 v72, v72
	v_exp_f32_e32 v73, v73
	v_exp_f32_e32 v74, v74
	v_exp_f32_e32 v75, v75
	s_waitcnt lgkmcnt(3)
	v_mfma_f32_32x32x16_bf16 v[132:147], v[164:167], v[112:115], v[132:147]
	ds_read_b128 v[164:167], v210 offset:32320
	v_add_f32_e32 v14, v14, v15
	v_add_f32_e32 v14, v14, v213
	v_exp_f32_e32 v76, v76
	v_exp_f32_e32 v77, v77
	s_setprio 2
	s_waitcnt lgkmcnt(3)
	v_mfma_f32_32x32x16_bf16 v[132:147], v[168:171], v[116:119], v[132:147]
	ds_read_b128 v[168:171], v210 offset:32352
	v_exp_f32_e32 v78, v78
	v_exp_f32_e32 v79, v79
	v_add_f32_e32 v15, v72, v73
	v_add_f32_e32 v213, v74, v75
	s_waitcnt lgkmcnt(3)
	v_mfma_f32_32x32x16_bf16 v[148:163], v[172:175], v[96:99], v[48:63]
	ds_read_b128 v[172:175], v210 offset:32384
	ds_read_b64_tr_b16 v[226:227], v211 offset:13312
	ds_read_b64_tr_b16 v[228:229], v211 offset:14848
	v_add_f32_e32 v200, v76, v77
	v_add_f32_e32 v201, v78, v79
	v_cvt_pk_bf16_f32 v68, v72, v73
	v_cvt_pk_bf16_f32 v69, v74, v75
	v_cvt_pk_bf16_f32 v70, v76, v77
	v_cvt_pk_bf16_f32 v71, v78, v79
	s_waitcnt lgkmcnt(5)
	v_mfma_f32_32x32x16_bf16 v[148:163], v[214:217], v[100:103], v[148:163]
	ds_read_b128 v[214:217], v210 offset:32416
	ds_read_b64_tr_b16 v[230:231], v211 offset:13376
	ds_read_b64_tr_b16 v[232:233], v211 offset:14912
	v_add_f32_e32 v15, v15, v213
	v_add_f32_e32 v200, v200, v201
	v_exp_f32_e32 v80, v80
	v_exp_f32_e32 v81, v81
	s_waitcnt lgkmcnt(7)
	v_mfma_f32_32x32x16_bf16 v[148:163], v[164:167], v[104:107], v[148:163]
	ds_read_b64_tr_b16 v[234:235], v211 offset:16384
	ds_read_b64_tr_b16 v[236:237], v211 offset:17920
	v_exp_f32_e32 v82, v82
	v_exp_f32_e32 v83, v83
	v_add_f32_e32 v14, v14, v15
	v_add_f32_e32 v14, v14, v200
	s_waitcnt lgkmcnt(8)
	v_mfma_f32_32x32x16_bf16 v[148:163], v[168:171], v[108:111], v[148:163]
	ds_read_b64_tr_b16 v[238:239], v211 offset:16448
	ds_read_b64_tr_b16 v[240:241], v211 offset:17984
	v_add_f32_e32 v15, v80, v81
	v_add_f32_e32 v213, v82, v83
	v_exp_f32_e32 v84, v84
	v_exp_f32_e32 v85, v85
	s_setprio 1
	s_waitcnt lgkmcnt(9)
	v_mfma_f32_32x32x16_bf16 v[148:163], v[172:175], v[112:115], v[148:163]
	v_exp_f32_e32 v86, v86
	v_exp_f32_e32 v87, v87
	v_add_f32_e32 v15, v15, v213
	v_add_f32_e32 v213, v84, v85
	s_waitcnt lgkmcnt(6)
	v_mfma_f32_32x32x16_bf16 v[148:163], v[214:217], v[116:119], v[148:163]
	v_add_f32_e32 v200, v86, v87
	v_cvt_pk_bf16_f32 v80, v80, v81
	v_cvt_pk_bf16_f32 v81, v82, v83
	v_cvt_pk_bf16_f32 v82, v84, v85
	v_cvt_pk_bf16_f32 v83, v86, v87
	v_mfma_f32_32x32x16_bf16 v[32:47], v[226:229], v[64:67], v[32:47]
	ds_read_b64_tr_b16 v[226:227], v211 offset:19456
	ds_read_b64_tr_b16 v[228:229], v211 offset:20992
	v_exp_f32_e32 v88, v88
	v_exp_f32_e32 v89, v89
	v_exp_f32_e32 v90, v90
	v_exp_f32_e32 v91, v91
	s_waitcnt lgkmcnt(6)
	v_mfma_f32_32x32x16_bf16 v[16:31], v[230:233], v[64:67], v[16:31]
	ds_read_b64_tr_b16 v[230:231], v211 offset:19520
	ds_read_b64_tr_b16 v[232:233], v211 offset:21056
	v_add_f32_e32 v213, v213, v200
	v_add_f32_e32 v15, v15, v213
	v_exp_f32_e32 v92, v92
	v_exp_f32_e32 v93, v93
	s_waitcnt lgkmcnt(6)
	v_mfma_f32_32x32x16_bf16 v[32:47], v[234:237], v[68:71], v[32:47]
	ds_read_b64_tr_b16 v[234:235], v211 offset:22528
	ds_read_b64_tr_b16 v[236:237], v211 offset:24064
	v_exp_f32_e32 v94, v94
	v_exp_f32_e32 v95, v95
	v_add_f32_e32 v213, v88, v89
	v_add_f32_e32 v200, v90, v91
	s_setprio 0
	s_waitcnt lgkmcnt(6)
	v_mfma_f32_32x32x16_bf16 v[16:31], v[238:241], v[68:71], v[16:31]
	ds_read_b64_tr_b16 v[238:239], v211 offset:22592
	ds_read_b64_tr_b16 v[240:241], v211 offset:24128
	s_cmp_lg_u32 s56, 0
	s_cbranch_scc1 .Lmla_mask0a
.Lmla_maskret0a:
	v_add_f32_e32 v201, v92, v93
	v_add_f32_e32 v250, v94, v95
	v_cvt_pk_bf16_f32 v84, v88, v89
	v_cvt_pk_bf16_f32 v85, v90, v91
	v_cvt_pk_bf16_f32 v86, v92, v93
	v_cvt_pk_bf16_f32 v87, v94, v95
	s_waitcnt lgkmcnt(6)
	v_mfma_f32_32x32x16_bf16 v[32:47], v[226:229], v[80:83], v[32:47]
	v_add_f32_e32 v213, v213, v200
	v_add_f32_e32 v201, v201, v250
	v_add_f32_e32 v14, v14, v15
	v_max3_f32 v251, v132, v133, v134
	v_max3_f32 v251, v251, v135, v136
	s_waitcnt lgkmcnt(4)
	v_mfma_f32_32x32x16_bf16 v[16:31], v[230:233], v[80:83], v[16:31]
	s_waitcnt vmcnt(5)
	ds_write_b128 v205, v[120:123] offset:0
	ds_write_b128 v205, v[246:249] offset:6656
	ds_write_b128 v206, v[124:127] offset:38912
	ds_write_b128 v206, v[222:225] offset:45056
	v_add_f32_e32 v213, v213, v201
	v_add_f32_e32 v14, v14, v213
	v_add_f32_e32 v209, v209, v14
	v_max3_f32 v251, v251, v137, v138
	v_max3_f32 v251, v251, v139, v140
	v_max3_f32 v251, v251, v141, v142
	s_waitcnt lgkmcnt(6)
	v_mfma_f32_32x32x16_bf16 v[32:47], v[234:237], v[84:87], v[32:47]
	v_max3_f32 v251, v251, v143, v144
	v_max3_f32 v251, v251, v145, v146
	v_max_f32_e32 v251, v251, v147
	v_max3_f32 v252, v148, v149, v150
	v_max3_f32 v252, v252, v151, v152
	s_waitcnt lgkmcnt(4)
	v_mfma_f32_32x32x16_bf16 v[16:31], v[238:241], v[84:87], v[16:31]
	ds_write_b128 v207, v[128:131] offset:128
	v_max3_f32 v252, v252, v153, v154
	v_max3_f32 v252, v252, v155, v156
	v_max3_f32 v252, v252, v157, v158
	v_max3_f32 v252, v252, v159, v160
	v_max3_f32 v252, v252, v161, v162
	v_max_f32_e32 v252, v252, v163
	v_max_f32_e32 v251, v251, v252
	v_mov_b32_e32 v252, v251
	s_nop 1
	v_permlane32_swap_b32_e32 v251, v252
	v_max_f32_e32 v251, v251, v252
	v_cmp_lt_f32_e32 vcc, 0x41000000, v251
	s_cmp_lg_u32 s26, 0
	s_cbranch_scc0 .Lmla_nr0a
	s_cbranch_vccnz .Lmla_rare0a

.Lmla_end0a:
.Lmla_it1a:
	s_add_i32 s66, s65, 1
	s_add_i32 s42, s66, 3
	s_min_u32 s42, s42, s44
	s_lshl_b64 s[6:7], s[42:43], 17
	v_lshl_add_u64 v[14:15], v[190:191], 0, s[6:7]
	s_lshl_b64 s[6:7], s[42:43], 12
	v_lshl_add_u64 v[252:253], v[194:195], 0, s[6:7]
	s_add_i32 s42, s66, 2
	s_min_u32 s42, s42, s44
	s_lshl_b64 s[6:7], s[42:43], 17
	v_lshl_add_u64 v[250:251], v[192:193], 0, s[6:7]
	s_mov_b64 s[4:5], 0x10000
	v_lshl_add_u64 v[200:201], v[250:251], 0, s[4:5]
	global_load_dwordx4 v[120:123], v[14:15], off
	v_lshl_add_u64 v[14:15], v[14:15], 0, s[4:5]
	global_load_dwordx4 v[124:127], v[250:251], off
	global_load_dwordx4 v[222:225], v[200:201], off
	global_load_dwordx4 v[246:249], v[14:15], off
	global_load_dwordx4 v[128:131], v[252:253], off
	s_cmp_ge_u32 s66, s45
	s_cbranch_scc1 .Lmla_skip1a
	s_add_i32 s41, s66, 1
	s_cmp_ge_u32 s41, s64
	s_cselect_b32 s7, 1, 0
	s_cmp_lt_u32 s41, s45
	s_cselect_b32 s26, 1, 0
	s_and_b32 s56, s7, s26
	s_lshl_b32 s27, s41, 6
	ds_read_b128 v[164:167], v210 offset:0
	ds_read_b128 v[168:171], v210 offset:32
	ds_read_b128 v[172:175], v210 offset:64
	ds_read_b128 v[214:217], v210 offset:96
	s_setprio 3
	v_exp_f32_e32 v132, v132
	v_exp_f32_e32 v133, v133
	v_exp_f32_e32 v134, v134
	v_exp_f32_e32 v135, v135
	s_waitcnt lgkmcnt(3)
	v_mfma_f32_32x32x16_bf16 v[64:79], v[164:167], v[96:99], v[48:63]
	ds_read_b128 v[164:167], v210 offset:128
	v_add_f32_e32 v14, v132, v133
	v_add_f32_e32 v15, v134, v135
	v_exp_f32_e32 v136, v136
	v_exp_f32_e32 v137, v137
	s_waitcnt lgkmcnt(3)
	v_mfma_f32_32x32x16_bf16 v[64:79], v[168:171], v[100:103], v[64:79]
	ds_read_b128 v[168:171], v210 offset:160
	v_exp_f32_e32 v138, v138
	v_exp_f32_e32 v139, v139
	v_add_f32_e32 v14, v14, v15
	v_add_f32_e32 v15, v136, v137
	s_waitcnt lgkmcnt(3)
	v_mfma_f32_32x32x16_bf16 v[64:79], v[172:175], v[104:107], v[64:79]
	ds_read_b128 v[172:175], v210 offset:6656
	v_add_f32_e32 v213, v138, v139
	v_cvt_pk_bf16_f32 v132, v132, v133
	v_cvt_pk_bf16_f32 v133, v134, v135
	v_cvt_pk_bf16_f32 v134, v136, v137
	v_cvt_pk_bf16_f32 v135, v138, v139
	s_waitcnt lgkmcnt(3)
	v_mfma_f32_32x32x16_bf16 v[64:79], v[214:217], v[108:111], v[64:79]
	ds_read_b128 v[214:217], v210 offset:6688
	v_exp_f32_e32 v140, v140
	v_exp_f32_e32 v141, v141
	v_exp_f32_e32 v142, v142
	v_exp_f32_e32 v143, v143
	s_waitcnt lgkmcnt(3)
	v_mfma_f32_32x32x16_bf16 v[64:79], v[164:167], v[112:115], v[64:79]
	ds_read_b128 v[164:167], v210 offset:6720
	v_add_f32_e32 v14, v14, v15
	v_add_f32_e32 v14, v14, v213
	v_exp_f32_e32 v144, v144
	v_exp_f32_e32 v145, v145
	s_setprio 2
	s_waitcnt lgkmcnt(3)
	v_mfma_f32_32x32x16_bf16 v[64:79], v[168:171], v[116:119], v[64:79]
	ds_read_b128 v[168:171], v210 offset:6752
	v_exp_f32_e32 v146, v146
	v_exp_f32_e32 v147, v147
	v_add_f32_e32 v15, v140, v141
	v_add_f32_e32 v213, v142, v143
	s_waitcnt lgkmcnt(3)
	v_mfma_f32_32x32x16_bf16 v[80:95], v[172:175], v[96:99], v[48:63]
	ds_read_b128 v[172:175], v210 offset:6784
	ds_read_b64_tr_b16 v[226:227], v211 offset:38912
	ds_read_b64_tr_b16 v[228:229], v211 offset:40448
	v_add_f32_e32 v200, v144, v145
	v_add_f32_e32 v201, v146, v147
	v_cvt_pk_bf16_f32 v136, v140, v141
	v_cvt_pk_bf16_f32 v137, v142, v143
	v_cvt_pk_bf16_f32 v138, v144, v145
	v_cvt_pk_bf16_f32 v139, v146, v147
	s_waitcnt lgkmcnt(5)
	v_mfma_f32_32x32x16_bf16 v[80:95], v[214:217], v[100:103], v[80:95]
	ds_read_b128 v[214:217], v210 offset:6816
	ds_read_b64_tr_b16 v[230:231], v211 offset:38976
	ds_read_b64_tr_b16 v[232:233], v211 offset:40512
	v_add_f32_e32 v15, v15, v213
	v_add_f32_e32 v200, v200, v201
	v_exp_f32_e32 v148, v148
	v_exp_f32_e32 v149, v149
	s_waitcnt lgkmcnt(7)
	v_mfma_f32_32x32x16_bf16 v[80:95], v[164:167], v[104:107], v[80:95]
	ds_read_b64_tr_b16 v[234:235], v211 offset:41984
	ds_read_b64_tr_b16 v[236:237], v211 offset:43520
	v_exp_f32_e32 v150, v150
	v_exp_f32_e32 v151, v151
	v_add_f32_e32 v14, v14, v15
	v_add_f32_e32 v14, v14, v200
	s_waitcnt lgkmcnt(8)
	v_mfma_f32_32x32x16_bf16 v[80:95], v[168:171], v[108:111], v[80:95]
	ds_read_b64_tr_b16 v[238:239], v211 offset:42048
	ds_read_b64_tr_b16 v[240:241], v211 offset:43584
	v_add_f32_e32 v15, v148, v149
	v_add_f32_e32 v213, v150, v151
	v_exp_f32_e32 v152, v152
	v_exp_f32_e32 v153, v153
	s_setprio 1
	s_waitcnt lgkmcnt(9)
	v_mfma_f32_32x32x16_bf16 v[80:95], v[172:175], v[112:115], v[80:95]
	v_exp_f32_e32 v154, v154
	v_exp_f32_e32 v155, v155
	v_add_f32_e32 v15, v15, v213
	v_add_f32_e32 v213, v152, v153
	s_waitcnt lgkmcnt(6)
	v_mfma_f32_32x32x16_bf16 v[80:95], v[214:217], v[116:119], v[80:95]
	v_add_f32_e32 v200, v154, v155
	v_cvt_pk_bf16_f32 v148, v148, v149
	v_cvt_pk_bf16_f32 v149, v150, v151
	v_cvt_pk_bf16_f32 v150, v152, v153
	v_cvt_pk_bf16_f32 v151, v154, v155
	v_mfma_f32_32x32x16_bf16 v[32:47], v[226:229], v[132:135], v[32:47]
	ds_read_b64_tr_b16 v[226:227], v211 offset:45056
	ds_read_b64_tr_b16 v[228:229], v211 offset:46592
	v_exp_f32_e32 v156, v156
	v_exp_f32_e32 v157, v157
	v_exp_f32_e32 v158, v158
	v_exp_f32_e32 v159, v159
	s_waitcnt lgkmcnt(6)
	v_mfma_f32_32x32x16_bf16 v[16:31], v[230:233], v[132:135], v[16:31]
	ds_read_b64_tr_b16 v[230:231], v211 offset:45120
	ds_read_b64_tr_b16 v[232:233], v211 offset:46656
	v_add_f32_e32 v213, v213, v200
	v_add_f32_e32 v15, v15, v213
	v_exp_f32_e32 v160, v160
	v_exp_f32_e32 v161, v161
	s_waitcnt lgkmcnt(6)
	v_mfma_f32_32x32x16_bf16 v[32:47], v[234:237], v[136:139], v[32:47]
	ds_read_b64_tr_b16 v[234:235], v211 offset:48128
	ds_read_b64_tr_b16 v[236:237], v211 offset:49664
	v_exp_f32_e32 v162, v162
	v_exp_f32_e32 v163, v163
	v_add_f32_e32 v213, v156, v157
	v_add_f32_e32 v200, v158, v159
	s_setprio 0
	s_waitcnt lgkmcnt(6)
	v_mfma_f32_32x32x16_bf16 v[16:31], v[238:241], v[136:139], v[16:31]
	ds_read_b64_tr_b16 v[238:239], v211 offset:48192
	ds_read_b64_tr_b16 v[240:241], v211 offset:49728
	s_cmp_lg_u32 s56, 0
	s_cbranch_scc1 .Lmla_mask1a
.Lmla_maskret1a:
	v_add_f32_e32 v201, v160, v161
	v_add_f32_e32 v250, v162, v163
	v_cvt_pk_bf16_f32 v152, v156, v157
	v_cvt_pk_bf16_f32 v153, v158, v159
	v_cvt_pk_bf16_f32 v154, v160, v161
	v_cvt_pk_bf16_f32 v155, v162, v163
	s_waitcnt lgkmcnt(6)
	v_mfma_f32_32x32x16_bf16 v[32:47], v[226:229], v[148:151], v[32:47]
	v_add_f32_e32 v213, v213, v200
	v_add_f32_e32 v201, v201, v250
	v_add_f32_e32 v14, v14, v15
	v_max3_f32 v251, v64, v65, v66
	v_max3_f32 v251, v251, v67, v68
	s_waitcnt lgkmcnt(4)
	v_mfma_f32_32x32x16_bf16 v[16:31], v[230:233], v[148:151], v[16:31]
	s_waitcnt vmcnt(5)
	ds_write_b128 v205, v[6:9] offset:25600
	ds_write_b128 v205, v[242:245] offset:32256
	ds_write_b128 v206, v[10:13] offset:13312
	ds_write_b128 v206, v[218:221] offset:19456
	v_add_f32_e32 v213, v213, v201
	v_add_f32_e32 v14, v14, v213
	v_add_f32_e32 v209, v209, v14
	v_max3_f32 v251, v251, v69, v70
	v_max3_f32 v251, v251, v71, v72
	v_max3_f32 v251, v251, v73, v74
	s_waitcnt lgkmcnt(6)
	v_mfma_f32_32x32x16_bf16 v[32:47], v[234:237], v[152:155], v[32:47]
	v_max3_f32 v251, v251, v75, v76
	v_max3_f32 v251, v251, v77, v78
	v_max_f32_e32 v251, v251, v79
	v_max3_f32 v252, v80, v81, v82
	v_max3_f32 v252, v252, v83, v84
	s_waitcnt lgkmcnt(4)
	v_mfma_f32_32x32x16_bf16 v[16:31], v[238:241], v[152:155], v[16:31]
	ds_write_b128 v207, v[2:5] offset:25728
	v_max3_f32 v252, v252, v85, v86
	v_max3_f32 v252, v252, v87, v88
	v_max3_f32 v252, v252, v89, v90
	v_max3_f32 v252, v252, v91, v92
	v_max3_f32 v252, v252, v93, v94
	v_max_f32_e32 v252, v252, v95
	v_max_f32_e32 v251, v251, v252
	v_mov_b32_e32 v252, v251
	s_nop 1
	v_permlane32_swap_b32_e32 v251, v252
	v_max_f32_e32 v251, v251, v252
	v_cmp_lt_f32_e32 vcc, 0x41000000, v251
	s_cmp_lg_u32 s26, 0
	s_cbranch_scc0 .Lmla_nr1a
	s_cbranch_vccnz .Lmla_rare1a

.Lmla_skip0a:
	s_waitcnt vmcnt(5)
	ds_write_b128 v205, v[120:123] offset:0
	ds_write_b128 v205, v[246:249] offset:6656
	ds_write_b128 v206, v[124:127] offset:38912
	ds_write_b128 v206, v[222:225] offset:45056
	ds_write_b128 v207, v[128:131] offset:128
	s_waitcnt lgkmcnt(0)
	s_barrier
	s_branch .Lmla_end0a

.Lmla_skip1a:
	s_waitcnt vmcnt(5)
	ds_write_b128 v205, v[6:9] offset:25600
	ds_write_b128 v205, v[242:245] offset:32256
	ds_write_b128 v206, v[10:13] offset:13312
	ds_write_b128 v206, v[218:221] offset:19456
	ds_write_b128 v207, v[2:5] offset:25728
	s_waitcnt lgkmcnt(0)
	s_barrier
	s_branch .Lmla_end1a

.Lmla_loopb:
.Lmla_it0b:
	s_cmp_ge_u32 s65, s45
	s_cbranch_scc1 .Lmla_skip0b
	s_add_i32 s41, s65, 1
	s_cmp_ge_u32 s41, s64
	s_cselect_b32 s7, 1, 0
	s_cmp_lt_u32 s41, s45
	s_cselect_b32 s26, 1, 0
	s_and_b32 s56, s7, s26
	s_lshl_b32 s27, s41, 6
	ds_read_b128 v[164:167], v210 offset:25600
	ds_read_b128 v[168:171], v210 offset:25632
	ds_read_b128 v[172:175], v210 offset:25664
	ds_read_b128 v[214:217], v210 offset:25696
	s_setprio 3
	v_exp_f32_e32 v64, v64
	v_exp_f32_e32 v65, v65
	v_exp_f32_e32 v66, v66
	v_exp_f32_e32 v67, v67
	s_waitcnt lgkmcnt(3)
	v_mfma_f32_32x32x16_bf16 v[132:147], v[164:167], v[96:99], v[48:63]
	ds_read_b128 v[164:167], v210 offset:25728
	v_add_f32_e32 v14, v64, v65
	v_add_f32_e32 v15, v66, v67
	v_exp_f32_e32 v68, v68
	v_exp_f32_e32 v69, v69
	s_waitcnt lgkmcnt(3)
	v_mfma_f32_32x32x16_bf16 v[132:147], v[168:171], v[100:103], v[132:147]
	ds_read_b128 v[168:171], v210 offset:25760
	v_exp_f32_e32 v70, v70
	v_exp_f32_e32 v71, v71
	v_add_f32_e32 v14, v14, v15
	v_add_f32_e32 v15, v68, v69
	s_waitcnt lgkmcnt(3)
	v_mfma_f32_32x32x16_bf16 v[132:147], v[172:175], v[104:107], v[132:147]
	ds_read_b128 v[172:175], v210 offset:32256
	v_add_f32_e32 v213, v70, v71
	v_cvt_pk_bf16_f32 v64, v64, v65
	v_cvt_pk_bf16_f32 v65, v66, v67
	v_cvt_pk_bf16_f32 v66, v68, v69
	v_cvt_pk_bf16_f32 v67, v70, v71
	s_waitcnt lgkmcnt(3)
	v_mfma_f32_32x32x16_bf16 v[132:147], v[214:217], v[108:111], v[132:147]
	ds_read_b128 v[214:217], v210 offset:32288
	v_exp_f32_e32 v72, v72
	v_exp_f32_e32 v73, v73
	v_exp_f32_e32 v74, v74
	v_exp_f32_e32 v75, v75
	s_waitcnt lgkmcnt(3)
	v_mfma_f32_32x32x16_bf16 v[132:147], v[164:167], v[112:115], v[132:147]
	ds_read_b128 v[164:167], v210 offset:32320
	v_add_f32_e32 v14, v14, v15
	v_add_f32_e32 v14, v14, v213
	v_exp_f32_e32 v76, v76
	v_exp_f32_e32 v77, v77
	s_setprio 2
	s_waitcnt lgkmcnt(3)
	v_mfma_f32_32x32x16_bf16 v[132:147], v[168:171], v[116:119], v[132:147]
	ds_read_b128 v[168:171], v210 offset:32352
	v_exp_f32_e32 v78, v78
	v_exp_f32_e32 v79, v79
	v_add_f32_e32 v15, v72, v73
	v_add_f32_e32 v213, v74, v75
	s_waitcnt lgkmcnt(3)
	v_mfma_f32_32x32x16_bf16 v[148:163], v[172:175], v[96:99], v[48:63]
	ds_read_b128 v[172:175], v210 offset:32384
	ds_read_b64_tr_b16 v[226:227], v211 offset:13312
	ds_read_b64_tr_b16 v[228:229], v211 offset:14848
	v_add_f32_e32 v200, v76, v77
	v_add_f32_e32 v201, v78, v79
	v_cvt_pk_bf16_f32 v68, v72, v73
	v_cvt_pk_bf16_f32 v69, v74, v75
	v_cvt_pk_bf16_f32 v70, v76, v77
	v_cvt_pk_bf16_f32 v71, v78, v79
	s_waitcnt lgkmcnt(5)
	v_mfma_f32_32x32x16_bf16 v[148:163], v[214:217], v[100:103], v[148:163]
	ds_read_b128 v[214:217], v210 offset:32416
	ds_read_b64_tr_b16 v[230:231], v211 offset:13376
	ds_read_b64_tr_b16 v[232:233], v211 offset:14912
	v_add_f32_e32 v15, v15, v213
	v_add_f32_e32 v200, v200, v201
	v_exp_f32_e32 v80, v80
	v_exp_f32_e32 v81, v81
	s_waitcnt lgkmcnt(7)
	v_mfma_f32_32x32x16_bf16 v[148:163], v[164:167], v[104:107], v[148:163]
	ds_read_b64_tr_b16 v[234:235], v211 offset:16384
	ds_read_b64_tr_b16 v[236:237], v211 offset:17920
	v_exp_f32_e32 v82, v82
	v_exp_f32_e32 v83, v83
	v_add_f32_e32 v14, v14, v15
	v_add_f32_e32 v14, v14, v200
	s_waitcnt lgkmcnt(8)
	v_mfma_f32_32x32x16_bf16 v[148:163], v[168:171], v[108:111], v[148:163]
	ds_read_b64_tr_b16 v[238:239], v211 offset:16448
	ds_read_b64_tr_b16 v[240:241], v211 offset:17984
	v_add_f32_e32 v15, v80, v81
	v_add_f32_e32 v213, v82, v83
	v_exp_f32_e32 v84, v84
	v_exp_f32_e32 v85, v85
	s_setprio 1
	s_waitcnt lgkmcnt(9)
	v_mfma_f32_32x32x16_bf16 v[148:163], v[172:175], v[112:115], v[148:163]
	v_exp_f32_e32 v86, v86
	v_exp_f32_e32 v87, v87
	v_add_f32_e32 v15, v15, v213
	v_add_f32_e32 v213, v84, v85
	s_waitcnt lgkmcnt(6)
	v_mfma_f32_32x32x16_bf16 v[148:163], v[214:217], v[116:119], v[148:163]
	v_add_f32_e32 v200, v86, v87
	v_cvt_pk_bf16_f32 v80, v80, v81
	v_cvt_pk_bf16_f32 v81, v82, v83
	v_cvt_pk_bf16_f32 v82, v84, v85
	v_cvt_pk_bf16_f32 v83, v86, v87
	v_mfma_f32_32x32x16_bf16 v[32:47], v[226:229], v[64:67], v[32:47]
	ds_read_b64_tr_b16 v[226:227], v211 offset:19456
	ds_read_b64_tr_b16 v[228:229], v211 offset:20992
	v_exp_f32_e32 v88, v88
	v_exp_f32_e32 v89, v89
	v_exp_f32_e32 v90, v90
	v_exp_f32_e32 v91, v91
	s_waitcnt lgkmcnt(6)
	v_mfma_f32_32x32x16_bf16 v[16:31], v[230:233], v[64:67], v[16:31]
	ds_read_b64_tr_b16 v[230:231], v211 offset:19520
	ds_read_b64_tr_b16 v[232:233], v211 offset:21056
	v_add_f32_e32 v213, v213, v200
	v_add_f32_e32 v15, v15, v213
	v_exp_f32_e32 v92, v92
	v_exp_f32_e32 v93, v93
	s_waitcnt lgkmcnt(6)
	v_mfma_f32_32x32x16_bf16 v[32:47], v[234:237], v[68:71], v[32:47]
	ds_read_b64_tr_b16 v[234:235], v211 offset:22528
	ds_read_b64_tr_b16 v[236:237], v211 offset:24064
	v_exp_f32_e32 v94, v94
	v_exp_f32_e32 v95, v95
	v_add_f32_e32 v213, v88, v89
	v_add_f32_e32 v200, v90, v91
	s_setprio 0
	s_waitcnt lgkmcnt(6)
	v_mfma_f32_32x32x16_bf16 v[16:31], v[238:241], v[68:71], v[16:31]
	ds_read_b64_tr_b16 v[238:239], v211 offset:22592
	ds_read_b64_tr_b16 v[240:241], v211 offset:24128
	s_cmp_lg_u32 s56, 0
	s_cbranch_scc1 .Lmla_mask0b
.Lmla_maskret0b:
	v_add_f32_e32 v201, v92, v93
	v_add_f32_e32 v250, v94, v95
	v_cvt_pk_bf16_f32 v84, v88, v89
	v_cvt_pk_bf16_f32 v85, v90, v91
	v_cvt_pk_bf16_f32 v86, v92, v93
	v_cvt_pk_bf16_f32 v87, v94, v95
	s_waitcnt lgkmcnt(6)
	v_mfma_f32_32x32x16_bf16 v[32:47], v[226:229], v[80:83], v[32:47]
	v_add_f32_e32 v213, v213, v200
	v_add_f32_e32 v201, v201, v250
	v_add_f32_e32 v14, v14, v15
	v_max3_f32 v251, v132, v133, v134
	v_max3_f32 v251, v251, v135, v136
	s_waitcnt lgkmcnt(4)
	v_mfma_f32_32x32x16_bf16 v[16:31], v[230:233], v[80:83], v[16:31]
	v_add_f32_e32 v213, v213, v201
	v_add_f32_e32 v14, v14, v213
	v_add_f32_e32 v209, v209, v14
	v_max3_f32 v251, v251, v137, v138
	v_max3_f32 v251, v251, v139, v140
	v_max3_f32 v251, v251, v141, v142
	s_waitcnt lgkmcnt(2)
	v_mfma_f32_32x32x16_bf16 v[32:47], v[234:237], v[84:87], v[32:47]
	v_max3_f32 v251, v251, v143, v144
	v_max3_f32 v251, v251, v145, v146
	v_max_f32_e32 v251, v251, v147
	v_max3_f32 v252, v148, v149, v150
	v_max3_f32 v252, v252, v151, v152
	s_waitcnt lgkmcnt(0)
	v_mfma_f32_32x32x16_bf16 v[16:31], v[238:241], v[84:87], v[16:31]
	v_max3_f32 v252, v252, v153, v154
	v_max3_f32 v252, v252, v155, v156
	v_max3_f32 v252, v252, v157, v158
	v_max3_f32 v252, v252, v159, v160
	v_max3_f32 v252, v252, v161, v162
	v_max_f32_e32 v252, v252, v163
	v_max_f32_e32 v251, v251, v252
	v_mov_b32_e32 v252, v251
	s_nop 1
	v_permlane32_swap_b32_e32 v251, v252
	v_max_f32_e32 v251, v251, v252
	v_cmp_lt_f32_e32 vcc, 0x41000000, v251
	s_cmp_lg_u32 s26, 0
	s_cbranch_scc0 .Lmla_nr0b
	s_cbranch_vccnz .Lmla_rare0b

.Lmla_end0b:
.Lmla_it1b:
	s_add_i32 s66, s65, 1
	s_cmp_ge_u32 s66, s45
	s_cbranch_scc1 .Lmla_skip1b
	s_add_i32 s41, s66, 1
	s_cmp_ge_u32 s41, s64
	s_cselect_b32 s7, 1, 0
	s_cmp_lt_u32 s41, s45
	s_cselect_b32 s26, 1, 0
	s_and_b32 s56, s7, s26
	s_lshl_b32 s27, s41, 6
	ds_read_b128 v[164:167], v210 offset:0
	ds_read_b128 v[168:171], v210 offset:32
	ds_read_b128 v[172:175], v210 offset:64
	ds_read_b128 v[214:217], v210 offset:96
	s_setprio 3
	v_exp_f32_e32 v132, v132
	v_exp_f32_e32 v133, v133
	v_exp_f32_e32 v134, v134
	v_exp_f32_e32 v135, v135
	s_waitcnt lgkmcnt(3)
	v_mfma_f32_32x32x16_bf16 v[64:79], v[164:167], v[96:99], v[48:63]
	ds_read_b128 v[164:167], v210 offset:128
	v_add_f32_e32 v14, v132, v133
	v_add_f32_e32 v15, v134, v135
	v_exp_f32_e32 v136, v136
	v_exp_f32_e32 v137, v137
	s_waitcnt lgkmcnt(3)
	v_mfma_f32_32x32x16_bf16 v[64:79], v[168:171], v[100:103], v[64:79]
	ds_read_b128 v[168:171], v210 offset:160
	v_exp_f32_e32 v138, v138
	v_exp_f32_e32 v139, v139
	v_add_f32_e32 v14, v14, v15
	v_add_f32_e32 v15, v136, v137
	s_waitcnt lgkmcnt(3)
	v_mfma_f32_32x32x16_bf16 v[64:79], v[172:175], v[104:107], v[64:79]
	ds_read_b128 v[172:175], v210 offset:6656
	v_add_f32_e32 v213, v138, v139
	v_cvt_pk_bf16_f32 v132, v132, v133
	v_cvt_pk_bf16_f32 v133, v134, v135
	v_cvt_pk_bf16_f32 v134, v136, v137
	v_cvt_pk_bf16_f32 v135, v138, v139
	s_waitcnt lgkmcnt(3)
	v_mfma_f32_32x32x16_bf16 v[64:79], v[214:217], v[108:111], v[64:79]
	ds_read_b128 v[214:217], v210 offset:6688
	v_exp_f32_e32 v140, v140
	v_exp_f32_e32 v141, v141
	v_exp_f32_e32 v142, v142
	v_exp_f32_e32 v143, v143
	s_waitcnt lgkmcnt(3)
	v_mfma_f32_32x32x16_bf16 v[64:79], v[164:167], v[112:115], v[64:79]
	ds_read_b128 v[164:167], v210 offset:6720
	v_add_f32_e32 v14, v14, v15
	v_add_f32_e32 v14, v14, v213
	v_exp_f32_e32 v144, v144
	v_exp_f32_e32 v145, v145
	s_setprio 2
	s_waitcnt lgkmcnt(3)
	v_mfma_f32_32x32x16_bf16 v[64:79], v[168:171], v[116:119], v[64:79]
	ds_read_b128 v[168:171], v210 offset:6752
	v_exp_f32_e32 v146, v146
	v_exp_f32_e32 v147, v147
	v_add_f32_e32 v15, v140, v141
	v_add_f32_e32 v213, v142, v143
	s_waitcnt lgkmcnt(3)
	v_mfma_f32_32x32x16_bf16 v[80:95], v[172:175], v[96:99], v[48:63]
	ds_read_b128 v[172:175], v210 offset:6784
	ds_read_b64_tr_b16 v[226:227], v211 offset:38912
	ds_read_b64_tr_b16 v[228:229], v211 offset:40448
	v_add_f32_e32 v200, v144, v145
	v_add_f32_e32 v201, v146, v147
	v_cvt_pk_bf16_f32 v136, v140, v141
	v_cvt_pk_bf16_f32 v137, v142, v143
	v_cvt_pk_bf16_f32 v138, v144, v145
	v_cvt_pk_bf16_f32 v139, v146, v147
	s_waitcnt lgkmcnt(5)
	v_mfma_f32_32x32x16_bf16 v[80:95], v[214:217], v[100:103], v[80:95]
	ds_read_b128 v[214:217], v210 offset:6816
	ds_read_b64_tr_b16 v[230:231], v211 offset:38976
	ds_read_b64_tr_b16 v[232:233], v211 offset:40512
	v_add_f32_e32 v15, v15, v213
	v_add_f32_e32 v200, v200, v201
	v_exp_f32_e32 v148, v148
	v_exp_f32_e32 v149, v149
	s_waitcnt lgkmcnt(7)
	v_mfma_f32_32x32x16_bf16 v[80:95], v[164:167], v[104:107], v[80:95]
	ds_read_b64_tr_b16 v[234:235], v211 offset:41984
	ds_read_b64_tr_b16 v[236:237], v211 offset:43520
	v_exp_f32_e32 v150, v150
	v_exp_f32_e32 v151, v151
	v_add_f32_e32 v14, v14, v15
	v_add_f32_e32 v14, v14, v200
	s_waitcnt lgkmcnt(8)
	v_mfma_f32_32x32x16_bf16 v[80:95], v[168:171], v[108:111], v[80:95]
	ds_read_b64_tr_b16 v[238:239], v211 offset:42048
	ds_read_b64_tr_b16 v[240:241], v211 offset:43584
	v_add_f32_e32 v15, v148, v149
	v_add_f32_e32 v213, v150, v151
	v_exp_f32_e32 v152, v152
	v_exp_f32_e32 v153, v153
	s_setprio 1
	s_waitcnt lgkmcnt(9)
	v_mfma_f32_32x32x16_bf16 v[80:95], v[172:175], v[112:115], v[80:95]
	v_exp_f32_e32 v154, v154
	v_exp_f32_e32 v155, v155
	v_add_f32_e32 v15, v15, v213
	v_add_f32_e32 v213, v152, v153
	s_waitcnt lgkmcnt(6)
	v_mfma_f32_32x32x16_bf16 v[80:95], v[214:217], v[116:119], v[80:95]
	v_add_f32_e32 v200, v154, v155
	v_cvt_pk_bf16_f32 v148, v148, v149
	v_cvt_pk_bf16_f32 v149, v150, v151
	v_cvt_pk_bf16_f32 v150, v152, v153
	v_cvt_pk_bf16_f32 v151, v154, v155
	v_mfma_f32_32x32x16_bf16 v[32:47], v[226:229], v[132:135], v[32:47]
	ds_read_b64_tr_b16 v[226:227], v211 offset:45056
	ds_read_b64_tr_b16 v[228:229], v211 offset:46592
	v_exp_f32_e32 v156, v156
	v_exp_f32_e32 v157, v157
	v_exp_f32_e32 v158, v158
	v_exp_f32_e32 v159, v159
	s_waitcnt lgkmcnt(6)
	v_mfma_f32_32x32x16_bf16 v[16:31], v[230:233], v[132:135], v[16:31]
	ds_read_b64_tr_b16 v[230:231], v211 offset:45120
	ds_read_b64_tr_b16 v[232:233], v211 offset:46656
	v_add_f32_e32 v213, v213, v200
	v_add_f32_e32 v15, v15, v213
	v_exp_f32_e32 v160, v160
	v_exp_f32_e32 v161, v161
	s_waitcnt lgkmcnt(6)
	v_mfma_f32_32x32x16_bf16 v[32:47], v[234:237], v[136:139], v[32:47]
	ds_read_b64_tr_b16 v[234:235], v211 offset:48128
	ds_read_b64_tr_b16 v[236:237], v211 offset:49664
	v_exp_f32_e32 v162, v162
	v_exp_f32_e32 v163, v163
	v_add_f32_e32 v213, v156, v157
	v_add_f32_e32 v200, v158, v159
	s_setprio 0
	s_waitcnt lgkmcnt(6)
	v_mfma_f32_32x32x16_bf16 v[16:31], v[238:241], v[136:139], v[16:31]
	ds_read_b64_tr_b16 v[238:239], v211 offset:48192
	ds_read_b64_tr_b16 v[240:241], v211 offset:49728
	s_cmp_lg_u32 s56, 0
	s_cbranch_scc1 .Lmla_mask1b
.Lmla_maskret1b:
	v_add_f32_e32 v201, v160, v161
	v_add_f32_e32 v250, v162, v163
	v_cvt_pk_bf16_f32 v152, v156, v157
	v_cvt_pk_bf16_f32 v153, v158, v159
	v_cvt_pk_bf16_f32 v154, v160, v161
	v_cvt_pk_bf16_f32 v155, v162, v163
	s_waitcnt lgkmcnt(6)
	v_mfma_f32_32x32x16_bf16 v[32:47], v[226:229], v[148:151], v[32:47]
	v_add_f32_e32 v213, v213, v200
	v_add_f32_e32 v201, v201, v250
	v_add_f32_e32 v14, v14, v15
	v_max3_f32 v251, v64, v65, v66
	v_max3_f32 v251, v251, v67, v68
	s_waitcnt lgkmcnt(4)
	v_mfma_f32_32x32x16_bf16 v[16:31], v[230:233], v[148:151], v[16:31]
	v_add_f32_e32 v213, v213, v201
	v_add_f32_e32 v14, v14, v213
	v_add_f32_e32 v209, v209, v14
	v_max3_f32 v251, v251, v69, v70
	v_max3_f32 v251, v251, v71, v72
	v_max3_f32 v251, v251, v73, v74
	s_waitcnt lgkmcnt(2)
	v_mfma_f32_32x32x16_bf16 v[32:47], v[234:237], v[152:155], v[32:47]
	v_max3_f32 v251, v251, v75, v76
	v_max3_f32 v251, v251, v77, v78
	v_max_f32_e32 v251, v251, v79
	v_max3_f32 v252, v80, v81, v82
	v_max3_f32 v252, v252, v83, v84
	s_waitcnt lgkmcnt(0)
	v_mfma_f32_32x32x16_bf16 v[16:31], v[238:241], v[152:155], v[16:31]
	v_max3_f32 v252, v252, v85, v86
	v_max3_f32 v252, v252, v87, v88
	v_max3_f32 v252, v252, v89, v90
	v_max3_f32 v252, v252, v91, v92
	v_max3_f32 v252, v252, v93, v94
	v_max_f32_e32 v252, v252, v95
	v_max_f32_e32 v251, v251, v252
	v_mov_b32_e32 v252, v251
	s_nop 1
	v_permlane32_swap_b32_e32 v251, v252
	v_max_f32_e32 v251, v251, v252
	v_cmp_lt_f32_e32 vcc, 0x41000000, v251
	s_cmp_lg_u32 s26, 0
	s_cbranch_scc0 .Lmla_nr1b
	s_cbranch_vccnz .Lmla_rare1b

.Lmla_skip0b:
	s_waitcnt lgkmcnt(0)
	s_barrier
	s_branch .Lmla_end0b
